# grid barrier: waiting workgroups poll the global generation word directly (one release hop less)
# speedup vs baseline: 1.0047x; 1.0047x over previous
; __device__ __forceinline__ unsigned xb_ld(unsigned* p)              { return __hip_atomic_load(p, __ATOMIC_RELAXED, __HIP_MEMORY_SCOPE_AGENT); }
; __device__ __forceinline__ unsigned xb_add(unsigned* p, unsigned v) { return __hip_atomic_fetch_add(p, v, __ATOMIC_RELAXED, __HIP_MEMORY_SCOPE_AGENT); }
; #define XB_SPIN(cond, bar) do { unsigned _sp = 0; while (cond) { __builtin_amdgcn_s_sleep(1); \
;     if ((++_sp & 255u) == 0u) { if (xb_ld(&(bar)[XB_TMO])) break; if (_sp > XB_SPIN_CAP) { atomicAdd(&(bar)[XB_TMO], 1u); break; } } } } while (0)
; __device__ __forceinline__ void xcd_barrier(const XcdBarrier& b) {
;     ...
;         const unsigned old = xb_add(&bar[XB_XSUB(b.x)], 1u);
;         const unsigned gen = old / nloc;
;         if (old + 1u == (gen + 1u) * nloc) {
;             __builtin_amdgcn_fence(__ATOMIC_RELEASE, "agent");
;             asm volatile("s_waitcnt vmcnt(0)" ::: "memory");
;             const unsigned og = xb_add(&bar[XB_TOP], 1u);
;             const unsigned tg = og / nx;
;             if (og + 1u == (tg + 1u) * nx) xb_add(&bar[XB_TOPGEN], 1u);
;             else XB_SPIN(xb_ld(&bar[XB_TOPGEN]) == tg, bar);
;             __builtin_amdgcn_fence(__ATOMIC_ACQUIRE, "agent");
;             xb_add(&bar[XB_XGEN(b.x)], 1u);
;             asm volatile("s_waitcnt vmcnt(0)" ::: "memory");
;         } else {
;             XB_SPIN(xb_ld(&bar[XB_XGEN(b.x)]) == gen, bar);
;             __builtin_amdgcn_fence(__ATOMIC_ACQUIRE, "agent");
;             asm volatile("s_waitcnt vmcnt(0)" ::: "memory");
;         }
.LBB0_87:
	s_or_b64 exec, exec, s[12:13]
	v_cvt_f32_u32_e32 v5, v3
	s_waitcnt vmcnt(0)
	v_readfirstlane_b32 s3, v4
	v_sub_u32_e32 v4, 0, v3
	v_rcp_iflag_f32_e32 v5, v5
	v_add_u32_e32 v6, s3, v2
	v_mul_f32_e32 v5, 0x4f7ffffe, v5
	v_cvt_u32_f32_e32 v5, v5
	v_mul_lo_u32 v2, v4, v5
	v_mul_hi_u32 v2, v5, v2
	v_add_u32_e32 v2, v5, v2
	v_mul_hi_u32 v2, v6, v2
	v_mul_lo_u32 v4, v2, v3
	v_sub_u32_e32 v4, v6, v4
	v_add_u32_e32 v5, 1, v2
	v_cmp_ge_u32_e32 vcc, v4, v3
	s_nop 1
	v_cndmask_b32_e32 v2, v2, v5, vcc
	v_sub_u32_e32 v5, v4, v3
	v_cndmask_b32_e32 v4, v4, v5, vcc
	v_add_u32_e32 v5, 1, v2
	v_cmp_ge_u32_e32 vcc, v4, v3
	v_add_u32_e32 v4, 1, v6
	s_nop 0
	v_cndmask_b32_e32 v2, v2, v5, vcc
	v_mul_lo_u32 v5, v3, v2
	v_add_u32_e32 v3, v5, v3
	v_cmp_ne_u32_e32 vcc, v4, v3
	s_and_saveexec_b64 s[10:11], vcc
	s_xor_b64 s[10:11], exec, s[10:11]
	s_cbranch_execz .LBB0_195
	s_waitcnt lgkmcnt(0)
	v_mov_b32_e32 v1, 0x7500
	global_load_dword v1, v1, s[22:23] sc1
	s_add_u32 s16, s22, 0x7500
	s_addc_u32 s17, s23, 0
	s_waitcnt vmcnt(0)
	v_cmp_eq_u32_e32 vcc, v1, v2
	s_and_saveexec_b64 s[12:13], vcc
	s_cbranch_execz .LBB0_194
	s_add_u32 s14, s22, 0x4200
	s_addc_u32 s15, s23, 0
	s_mov_b32 s3, 1
	s_mov_b64 s[28:29], 0
	v_mov_b32_e32 v1, 0
	s_branch .LBB0_91

; __device__ __forceinline__ unsigned xb_ld(unsigned* p)              { return __hip_atomic_load(p, __ATOMIC_RELAXED, __HIP_MEMORY_SCOPE_AGENT); }
; __device__ __forceinline__ unsigned xb_add(unsigned* p, unsigned v) { return __hip_atomic_fetch_add(p, v, __ATOMIC_RELAXED, __HIP_MEMORY_SCOPE_AGENT); }
; #define XB_SPIN(cond, bar) do { unsigned _sp = 0; while (cond) { __builtin_amdgcn_s_sleep(1); \
;     if ((++_sp & 255u) == 0u) { if (xb_ld(&(bar)[XB_TMO])) break; if (_sp > XB_SPIN_CAP) { atomicAdd(&(bar)[XB_TMO], 1u); break; } } } } while (0)
; __device__ __forceinline__ void xcd_barrier(const XcdBarrier& b) {
;     ...
;         const unsigned old = xb_add(&bar[XB_XSUB(b.x)], 1u);
;         const unsigned gen = old / nloc;
;         if (old + 1u == (gen + 1u) * nloc) {
;             __builtin_amdgcn_fence(__ATOMIC_RELEASE, "agent");
;             asm volatile("s_waitcnt vmcnt(0)" ::: "memory");
;             const unsigned og = xb_add(&bar[XB_TOP], 1u);
;             const unsigned tg = og / nx;
;             if (og + 1u == (tg + 1u) * nx) xb_add(&bar[XB_TOPGEN], 1u);
;             else XB_SPIN(xb_ld(&bar[XB_TOPGEN]) == tg, bar);
;             __builtin_amdgcn_fence(__ATOMIC_ACQUIRE, "agent");
;             xb_add(&bar[XB_XGEN(b.x)], 1u);
;             asm volatile("s_waitcnt vmcnt(0)" ::: "memory");
;         } else {
;             XB_SPIN(xb_ld(&bar[XB_XGEN(b.x)]) == gen, bar);
;             __builtin_amdgcn_fence(__ATOMIC_ACQUIRE, "agent");
;             asm volatile("s_waitcnt vmcnt(0)" ::: "memory");
;         }
.LBB0_326:
	s_or_b64 exec, exec, s[12:13]
	v_cvt_f32_u32_e32 v5, v3
	s_waitcnt vmcnt(0)
	v_readfirstlane_b32 s3, v4
	v_sub_u32_e32 v4, 0, v3
	v_rcp_iflag_f32_e32 v5, v5
	v_add_u32_e32 v6, s3, v2
	v_mul_f32_e32 v5, 0x4f7ffffe, v5
	v_cvt_u32_f32_e32 v5, v5
	v_mul_lo_u32 v2, v4, v5
	v_mul_hi_u32 v2, v5, v2
	v_add_u32_e32 v2, v5, v2
	v_mul_hi_u32 v2, v6, v2
	v_mul_lo_u32 v4, v2, v3
	v_sub_u32_e32 v4, v6, v4
	v_add_u32_e32 v5, 1, v2
	v_cmp_ge_u32_e32 vcc, v4, v3
	s_nop 1
	v_cndmask_b32_e32 v2, v2, v5, vcc
	v_sub_u32_e32 v5, v4, v3
	v_cndmask_b32_e32 v4, v4, v5, vcc
	v_add_u32_e32 v5, 1, v2
	v_cmp_ge_u32_e32 vcc, v4, v3
	v_add_u32_e32 v4, 1, v6
	s_nop 0
	v_cndmask_b32_e32 v2, v2, v5, vcc
	v_mul_lo_u32 v5, v3, v2
	v_add_u32_e32 v3, v5, v3
	v_cmp_ne_u32_e32 vcc, v4, v3
	s_and_saveexec_b64 s[10:11], vcc
	s_xor_b64 s[10:11], exec, s[10:11]
	s_cbranch_execz .LBB0_340
	s_waitcnt lgkmcnt(0)
	v_mov_b32_e32 v1, 0x7500
	global_load_dword v1, v1, s[22:23] sc1
	s_add_u32 s16, s22, 0x7500
	s_addc_u32 s17, s23, 0
	s_waitcnt vmcnt(0)
	v_cmp_eq_u32_e32 vcc, v1, v2
	s_and_saveexec_b64 s[12:13], vcc
	s_cbranch_execz .LBB0_339
	s_add_u32 s14, s22, 0x4200
	s_addc_u32 s15, s23, 0
	s_mov_b32 s3, 1
	s_mov_b64 s[36:37], 0
	v_mov_b32_e32 v1, 0
	s_branch .LBB0_330

; __device__ __forceinline__ unsigned xb_ld(unsigned* p)              { return __hip_atomic_load(p, __ATOMIC_RELAXED, __HIP_MEMORY_SCOPE_AGENT); }
; __device__ __forceinline__ unsigned xb_add(unsigned* p, unsigned v) { return __hip_atomic_fetch_add(p, v, __ATOMIC_RELAXED, __HIP_MEMORY_SCOPE_AGENT); }
; #define XB_SPIN(cond, bar) do { unsigned _sp = 0; while (cond) { __builtin_amdgcn_s_sleep(1); \
;     if ((++_sp & 255u) == 0u) { if (xb_ld(&(bar)[XB_TMO])) break; if (_sp > XB_SPIN_CAP) { atomicAdd(&(bar)[XB_TMO], 1u); break; } } } } while (0)
; __device__ __forceinline__ void xcd_barrier(const XcdBarrier& b) {
;     ...
;         const unsigned old = xb_add(&bar[XB_XSUB(b.x)], 1u);
;         const unsigned gen = old / nloc;
;         if (old + 1u == (gen + 1u) * nloc) {
;             __builtin_amdgcn_fence(__ATOMIC_RELEASE, "agent");
;             asm volatile("s_waitcnt vmcnt(0)" ::: "memory");
;             const unsigned og = xb_add(&bar[XB_TOP], 1u);
;             const unsigned tg = og / nx;
;             if (og + 1u == (tg + 1u) * nx) xb_add(&bar[XB_TOPGEN], 1u);
;             else XB_SPIN(xb_ld(&bar[XB_TOPGEN]) == tg, bar);
;             __builtin_amdgcn_fence(__ATOMIC_ACQUIRE, "agent");
;             xb_add(&bar[XB_XGEN(b.x)], 1u);
;             asm volatile("s_waitcnt vmcnt(0)" ::: "memory");
;         } else {
;             XB_SPIN(xb_ld(&bar[XB_XGEN(b.x)]) == gen, bar);
;             __builtin_amdgcn_fence(__ATOMIC_ACQUIRE, "agent");
;             asm volatile("s_waitcnt vmcnt(0)" ::: "memory");
;         }
.LBB0_1839:
	s_or_b64 exec, exec, s[12:13]
	v_cvt_f32_u32_e32 v6, v4
	s_waitcnt vmcnt(0)
	v_readfirstlane_b32 s3, v5
	v_sub_u32_e32 v5, 0, v4
	v_rcp_iflag_f32_e32 v6, v6
	v_add_u32_e32 v7, s3, v3
	v_mul_f32_e32 v6, 0x4f7ffffe, v6
	v_cvt_u32_f32_e32 v6, v6
	v_mul_lo_u32 v3, v5, v6
	v_mul_hi_u32 v3, v6, v3
	v_add_u32_e32 v3, v6, v3
	v_mul_hi_u32 v3, v7, v3
	v_mul_lo_u32 v5, v3, v4
	v_sub_u32_e32 v5, v7, v5
	v_add_u32_e32 v6, 1, v3
	v_cmp_ge_u32_e32 vcc, v5, v4
	s_nop 1
	v_cndmask_b32_e32 v3, v3, v6, vcc
	v_sub_u32_e32 v6, v5, v4
	v_cndmask_b32_e32 v5, v5, v6, vcc
	v_add_u32_e32 v6, 1, v3
	v_cmp_ge_u32_e32 vcc, v5, v4
	v_add_u32_e32 v5, 1, v7
	s_nop 0
	v_cndmask_b32_e32 v3, v3, v6, vcc
	v_mul_lo_u32 v6, v4, v3
	v_add_u32_e32 v4, v6, v4
	v_cmp_ne_u32_e32 vcc, v5, v4
	s_and_saveexec_b64 s[10:11], vcc
	s_xor_b64 s[10:11], exec, s[10:11]
	s_cbranch_execz .LBB0_1853
	s_waitcnt lgkmcnt(0)
	v_mov_b32_e32 v2, 0x7500
	global_load_dword v2, v2, s[22:23] sc1
	s_add_u32 s16, s22, 0x7500
	s_addc_u32 s17, s23, 0
	s_waitcnt vmcnt(0)
	v_cmp_eq_u32_e32 vcc, v2, v3
	s_and_saveexec_b64 s[12:13], vcc
	s_cbranch_execz .LBB0_1852
	s_add_u32 s14, s22, 0x4200
	s_addc_u32 s15, s23, 0
	s_mov_b32 s3, 1
	s_mov_b64 s[30:31], 0
	v_mov_b32_e32 v2, 0
	s_branch .LBB0_1843

; __device__ __forceinline__ unsigned xb_ld(unsigned* p)              { return __hip_atomic_load(p, __ATOMIC_RELAXED, __HIP_MEMORY_SCOPE_AGENT); }
; __device__ __forceinline__ unsigned xb_add(unsigned* p, unsigned v) { return __hip_atomic_fetch_add(p, v, __ATOMIC_RELAXED, __HIP_MEMORY_SCOPE_AGENT); }
; #define XB_SPIN(cond, bar) do { unsigned _sp = 0; while (cond) { __builtin_amdgcn_s_sleep(1); \
;     if ((++_sp & 255u) == 0u) { if (xb_ld(&(bar)[XB_TMO])) break; if (_sp > XB_SPIN_CAP) { atomicAdd(&(bar)[XB_TMO], 1u); break; } } } } while (0)
; __device__ __forceinline__ void xcd_barrier(const XcdBarrier& b) {
;     ...
;         const unsigned old = xb_add(&bar[XB_XSUB(b.x)], 1u);
;         const unsigned gen = old / nloc;
;         if (old + 1u == (gen + 1u) * nloc) {
;             __builtin_amdgcn_fence(__ATOMIC_RELEASE, "agent");
;             asm volatile("s_waitcnt vmcnt(0)" ::: "memory");
;             const unsigned og = xb_add(&bar[XB_TOP], 1u);
;             const unsigned tg = og / nx;
;             if (og + 1u == (tg + 1u) * nx) xb_add(&bar[XB_TOPGEN], 1u);
;             else XB_SPIN(xb_ld(&bar[XB_TOPGEN]) == tg, bar);
;             __builtin_amdgcn_fence(__ATOMIC_ACQUIRE, "agent");
;             xb_add(&bar[XB_XGEN(b.x)], 1u);
;             asm volatile("s_waitcnt vmcnt(0)" ::: "memory");
;         } else {
;             XB_SPIN(xb_ld(&bar[XB_XGEN(b.x)]) == gen, bar);
;             __builtin_amdgcn_fence(__ATOMIC_ACQUIRE, "agent");
;             asm volatile("s_waitcnt vmcnt(0)" ::: "memory");
;         }
.LBB0_1956:
	s_or_b64 exec, exec, s[8:9]
	v_cvt_f32_u32_e32 v5, v3
	s_waitcnt vmcnt(0)
	v_readfirstlane_b32 s6, v4
	v_sub_u32_e32 v4, 0, v3
	v_rcp_iflag_f32_e32 v5, v5
	v_add_u32_e32 v6, s6, v2
	v_mul_f32_e32 v5, 0x4f7ffffe, v5
	v_cvt_u32_f32_e32 v5, v5
	v_mul_lo_u32 v2, v4, v5
	v_mul_hi_u32 v2, v5, v2
	v_add_u32_e32 v2, v5, v2
	v_mul_hi_u32 v2, v6, v2
	v_mul_lo_u32 v4, v2, v3
	v_sub_u32_e32 v4, v6, v4
	v_add_u32_e32 v5, 1, v2
	v_cmp_ge_u32_e32 vcc, v4, v3
	s_nop 1
	v_cndmask_b32_e32 v2, v2, v5, vcc
	v_sub_u32_e32 v5, v4, v3
	v_cndmask_b32_e32 v4, v4, v5, vcc
	v_add_u32_e32 v5, 1, v2
	v_cmp_ge_u32_e32 vcc, v4, v3
	v_add_u32_e32 v4, 1, v6
	s_nop 0
	v_cndmask_b32_e32 v2, v2, v5, vcc
	v_mul_lo_u32 v5, v3, v2
	v_add_u32_e32 v3, v5, v3
	v_cmp_ne_u32_e32 vcc, v4, v3
	s_and_saveexec_b64 s[6:7], vcc
	s_xor_b64 s[6:7], exec, s[6:7]
	s_cbranch_execz .LBB0_1970
	s_waitcnt lgkmcnt(0)
	v_mov_b32_e32 v1, 0x7500
	global_load_dword v1, v1, s[22:23] sc1
	s_add_u32 s12, s22, 0x7500
	s_addc_u32 s13, s23, 0
	s_waitcnt vmcnt(0)
	v_cmp_eq_u32_e32 vcc, v1, v2
	s_and_saveexec_b64 s[8:9], vcc
	s_cbranch_execz .LBB0_1969
	s_add_u32 s10, s22, 0x4200
	s_addc_u32 s11, s23, 0
	s_mov_b32 s19, 1
	s_mov_b64 s[14:15], 0
	v_mov_b32_e32 v1, 0
	s_branch .LBB0_1960
